# lever 7 instruction selection: scan state-wave k^T loads addressed as scalar row base + one per-lane 32-bit offset (saddr form), replacing v_mad_i64 and 7 v_add_co/s_nop/v_addc triples per step, both
# speedup vs baseline: 1.0004x; 1.0004x over previous
.LBB0_250:
	v_mov_b32_e32 v4, v3
	v_mov_b32_e32 v5, v3
	v_mov_b32_e32 v100, v3
	v_mov_b32_e32 v101, v3
	v_lshl_add_u64 v[146:147], v[2:3], 1, s[56:57]
	s_lshl_b32 s22, s25, 9
	s_lshl_b32 s23, s60, 6
	v_lshlrev_b32_e32 v244, 1, v2
	v_mov_b32_e32 v2, v3
	v_mov_b32_e32 v98, v3
	v_mov_b32_e32 v99, v3
	v_mov_b64_e32 v[132:133], v[100:101]
	v_mov_b64_e32 v[104:105], v[100:101]
	v_mov_b64_e32 v[136:137], v[100:101]
	v_mov_b64_e32 v[108:109], v[100:101]
	v_mov_b64_e32 v[120:121], v[100:101]
	v_mov_b64_e32 v[112:113], v[100:101]
	v_mov_b64_e32 v[116:117], v[100:101]
	v_mov_b64_e32 v[80:81], v[4:5]
	s_add_i32 s22, s22, s0
	v_lshl_add_u32 v165, s60, 7, v207
	v_lshl_add_u32 v166, s60, 8, v206
	s_mov_b32 s74, 0
	s_lshl_b32 s23, s23, 2
	v_mov_b64_e32 v[130:131], v[98:99]
	v_mov_b64_e32 v[102:103], v[98:99]
	v_mov_b64_e32 v[134:135], v[98:99]
	v_mov_b64_e32 v[106:107], v[98:99]
	v_mov_b64_e32 v[118:119], v[98:99]
	v_mov_b64_e32 v[110:111], v[98:99]
	v_mov_b64_e32 v[114:115], v[98:99]
	v_mov_b64_e32 v[78:79], v[2:3]
	v_and_b32_e32 v240, 63, v151
	v_bfe_u32 v241, v240, 3, 2
	s_lshr_b32 s98, s92, 3
	s_and_b32 s98, s98, 15
	s_lshl_b32 s98, s98, 2
	v_add_u32_e32 v241, s98, v241
	v_mul_u32_u24_e32 v241, 0x6080, v241
	v_and_b32_e32 v242, 3, v240
	v_lshlrev_b32_e32 v242, 7, v242
	v_bfe_u32 v243, v240, 2, 1
	v_lshlrev_b32_e32 v243, 11, v243
	s_mul_i32 s99, s0, 512
	v_add3_u32 v240, v241, v242, v243
	v_add_u32_e32 v240, s99, v240
	s_branch .LBB0_252

.LBB0_252:
	s_min_u32 s98, s74, 0x7d
	s_add_i32 s98, s98, 2
	s_lshl_b32 s99, s98, 6
	s_add_i32 s99, s99, s94
	s_mul_i32 s100, s99, 0x6080
	s_add_u32 s100, s100, s56
	s_addc_u32 s101, s57, 0
	s_waitcnt lgkmcnt(0)
	s_barrier
	global_load_dwordx4 v[142:145], v244, s[100:101]
	s_add_u32 s100, s100, 0xc000
	s_addc_u32 s101, s101, 0
	global_load_dwordx4 v[138:141], v244, s[100:101] offset:256
	s_add_u32 s100, s100, 0xc000
	s_addc_u32 s101, s101, 0
	global_load_dwordx4 v[126:129], v244, s[100:101] offset:512
	s_add_u32 s100, s100, 0xc000
	s_addc_u32 s101, s101, 0
	global_load_dwordx4 v[122:125], v244, s[100:101] offset:768
	s_add_u32 s100, s100, 0xc000
	s_addc_u32 s101, s101, 0
	global_load_dwordx4 v[94:97], v244, s[100:101] offset:1024
	s_add_u32 s100, s100, 0xc000
	s_addc_u32 s101, s101, 0
	global_load_dwordx4 v[90:93], v244, s[100:101] offset:1280
	s_add_u32 s100, s100, 0xc000
	s_addc_u32 s101, s101, 0
	global_load_dwordx4 v[86:89], v244, s[100:101] offset:1536
	s_add_u32 s100, s100, 0xc000
	s_addc_u32 s101, s101, 0
	global_load_dwordx4 v[82:85], v244, s[100:101] offset:1792
	s_and_b64 vcc, exec, s[16:17]
	s_cbranch_vccnz .Lsa_skip_p3a
	s_lshl_b32 s98, s98, 2
	s_add_i32 s100, s98, s22
	s_ashr_i32 s101, s100, 31
	s_lshl_b64 s[100:101], s[100:101], 10
	v_lshl_add_u64 v[78:79], v[158:159], 0, s[100:101]
	global_load_dwordx4 v[78:81], v[78:79], off
	s_min_u32 s99, s74, 0x7d
	s_add_i32 s99, s99, 4
	s_min_u32 s99, s99, 0x7f
	s_lshl_b32 s99, s99, 6
	s_add_i32 s99, s99, s94
	s_mul_hi_u32 s101, s99, 0x6080
	s_mul_i32 s100, s99, 0x6080
	s_add_u32 s100, s100, s56
	s_addc_u32 s101, s101, s57
	global_load_dword v241, v240, s[100:101]
.Lsa_skip_p3a:
.LBB0_254:
	s_and_b32 s95, s74, 1
	s_lshl_b32 s27, s95, 10
	s_mul_i32 s26, s95, 0x1200
	s_add_i32 s86, s27, 0
	v_add_u32_e32 v2, s26, v206
	s_add_i32 s26, s23, s86
	v_add_u32_e32 v5, v2, v208
	v_lshl_add_u32 v2, v205, 2, s26
	ds_read_b128 v[168:171], v2 offset:43008
	ds_read_b128 v[172:175], v5 offset:33792
	ds_read_b128 v[176:179], v5 offset:33856
	ds_read_b128 v[180:183], v5 offset:36096
	ds_read_b128 v[184:187], v5 offset:36160
	s_xor_b32 s96, s95, 1
	s_waitcnt lgkmcnt(4)
	v_pk_mul_f32 v[116:117], v[116:117], v[170:171]
	v_pk_mul_f32 v[114:115], v[114:115], v[168:169]
	v_pk_mul_f32 v[112:113], v[112:113], v[170:171]
	v_pk_mul_f32 v[110:111], v[110:111], v[168:169]
	s_waitcnt vmcnt(15) lgkmcnt(3)
	v_mfma_f32_16x16x32_bf16 v[114:117], v[50:53], v[172:175], v[114:117]
	s_mul_i32 s26, s96, 0x4200
	v_add_u32_e32 v4, s26, v165
	v_add_u32_e32 v4, v4, v209
	s_waitcnt lgkmcnt(1)
	v_mfma_f32_16x16x32_bf16 v[50:53], v[50:53], v[180:183], v[110:113]
	s_and_b64 vcc, exec, s[16:17]
	s_lshl_b32 s75, s96, 10
	s_waitcnt vmcnt(14)
	v_mfma_f32_16x16x32_bf16 v[114:117], v[54:57], v[176:179], v[114:117]
	s_waitcnt lgkmcnt(0)
	v_mfma_f32_16x16x32_bf16 v[110:113], v[54:57], v[184:187], v[50:53]
	s_nop 5
	v_cvt_pk_bf16_f32 v232, v114, v115
	v_cvt_pk_bf16_f32 v233, v116, v117
	v_cvt_pk_bf16_f32 v50, v110, v111
	v_cvt_pk_bf16_f32 v51, v112, v113
	ds_write_b64 v4, v[232:233]
	ds_write_b64 v4, v[50:51] offset:8448
	ds_read_b128 v[50:53], v2 offset:43072
	s_waitcnt lgkmcnt(0)
	v_pk_mul_f32 v[56:57], v[120:121], v[52:53]
	v_pk_mul_f32 v[54:55], v[118:119], v[50:51]
	v_pk_mul_f32 v[52:53], v[108:109], v[52:53]
	v_pk_mul_f32 v[50:51], v[106:107], v[50:51]
	s_waitcnt vmcnt(13)
	v_mfma_f32_16x16x32_bf16 v[54:57], v[38:41], v[172:175], v[54:57]
	v_mfma_f32_16x16x32_bf16 v[38:41], v[38:41], v[180:183], v[50:53]
	s_waitcnt vmcnt(12)
	v_mfma_f32_16x16x32_bf16 v[118:121], v[42:45], v[176:179], v[54:57]
	v_mfma_f32_16x16x32_bf16 v[106:109], v[42:45], v[184:187], v[38:41]
	s_nop 6
	v_cvt_pk_bf16_f32 v50, v118, v119
	v_cvt_pk_bf16_f32 v51, v120, v121
	v_cvt_pk_bf16_f32 v38, v106, v107
	v_cvt_pk_bf16_f32 v39, v108, v109
	ds_write_b64 v4, v[50:51] offset:32
	ds_write_b64 v4, v[38:39] offset:8480
	ds_read_b128 v[38:41], v2 offset:43136
	s_waitcnt lgkmcnt(0)
	v_pk_mul_f32 v[44:45], v[136:137], v[40:41]
	v_pk_mul_f32 v[42:43], v[134:135], v[38:39]
	v_pk_mul_f32 v[40:41], v[104:105], v[40:41]
	v_pk_mul_f32 v[38:39], v[102:103], v[38:39]
	s_waitcnt vmcnt(11)
	v_mfma_f32_16x16x32_bf16 v[42:45], v[26:29], v[172:175], v[42:45]
	v_mfma_f32_16x16x32_bf16 v[26:29], v[26:29], v[180:183], v[38:41]
	s_waitcnt vmcnt(10)
	v_mfma_f32_16x16x32_bf16 v[134:137], v[30:33], v[176:179], v[42:45]
	v_mfma_f32_16x16x32_bf16 v[102:105], v[30:33], v[184:187], v[26:29]
	s_nop 6
	v_cvt_pk_bf16_f32 v38, v134, v135
	v_cvt_pk_bf16_f32 v39, v136, v137
	v_cvt_pk_bf16_f32 v26, v102, v103
	v_cvt_pk_bf16_f32 v27, v104, v105
	ds_write_b64 v4, v[38:39] offset:64
	ds_write_b64 v4, v[26:27] offset:8512
	ds_read_b128 v[26:29], v2 offset:43200
	s_waitcnt lgkmcnt(0)
	v_pk_mul_f32 v[32:33], v[132:133], v[28:29]
	v_pk_mul_f32 v[30:31], v[130:131], v[26:27]
	v_pk_mul_f32 v[28:29], v[100:101], v[28:29]
	v_pk_mul_f32 v[26:27], v[98:99], v[26:27]
	s_waitcnt vmcnt(9)
	v_mfma_f32_16x16x32_bf16 v[30:33], v[18:21], v[172:175], v[30:33]
	v_mfma_f32_16x16x32_bf16 v[18:21], v[18:21], v[180:183], v[26:29]
	s_waitcnt vmcnt(8)
	v_mfma_f32_16x16x32_bf16 v[130:133], v[22:25], v[176:179], v[30:33]
	v_mfma_f32_16x16x32_bf16 v[98:101], v[22:25], v[184:187], v[18:21]
	s_nop 6
	v_cvt_pk_bf16_f32 v26, v130, v131
	v_cvt_pk_bf16_f32 v27, v132, v133
	v_cvt_pk_bf16_f32 v18, v98, v99
	v_cvt_pk_bf16_f32 v19, v100, v101
	ds_write_b64 v4, v[26:27] offset:96
	ds_write_b64 v4, v[18:19] offset:8544
	s_cbranch_vccnz .LBB0_256
	v_add_u32_e32 v18, s75, v204
	s_waitcnt vmcnt(8)
	ds_write_b128 v18, v[58:61] offset:43008
.LBB0_256:
	s_min_u32 s98, s74, 0x7c
	s_add_i32 s98, s98, 3
	s_lshl_b32 s99, s98, 6
	s_add_i32 s99, s99, s94
	s_mul_i32 s100, s99, 0x6080
	s_add_u32 s100, s100, s56
	s_addc_u32 s101, s57, 0
	s_waitcnt lgkmcnt(0)
	s_barrier
	global_load_dwordx4 v[50:53], v244, s[100:101]
	s_add_u32 s100, s100, 0xc000
	s_addc_u32 s101, s101, 0
	global_load_dwordx4 v[54:57], v244, s[100:101] offset:256
	s_add_u32 s100, s100, 0xc000
	s_addc_u32 s101, s101, 0
	global_load_dwordx4 v[38:41], v244, s[100:101] offset:512
	s_add_u32 s100, s100, 0xc000
	s_addc_u32 s101, s101, 0
	global_load_dwordx4 v[42:45], v244, s[100:101] offset:768
	s_add_u32 s100, s100, 0xc000
	s_addc_u32 s101, s101, 0
	global_load_dwordx4 v[26:29], v244, s[100:101] offset:1024
	s_add_u32 s100, s100, 0xc000
	s_addc_u32 s101, s101, 0
	global_load_dwordx4 v[30:33], v244, s[100:101] offset:1280
	s_add_u32 s100, s100, 0xc000
	s_addc_u32 s101, s101, 0
	global_load_dwordx4 v[18:21], v244, s[100:101] offset:1536
	s_add_u32 s100, s100, 0xc000
	s_addc_u32 s101, s101, 0
	global_load_dwordx4 v[22:25], v244, s[100:101] offset:1792
	s_and_b64 vcc, exec, s[16:17]
	s_cbranch_vccnz .Lsa_skip_p3b
	s_lshl_b32 s98, s98, 2
	s_add_i32 s100, s98, s22
	s_ashr_i32 s101, s100, 31
	s_lshl_b64 s[100:101], s[100:101], 10
	v_lshl_add_u64 v[6:7], v[158:159], 0, s[100:101]
	global_load_dwordx4 v[6:9], v[6:7], off
	s_min_u32 s99, s74, 0x7c
	s_add_i32 s99, s99, 5
	s_min_u32 s99, s99, 0x7f
	s_lshl_b32 s99, s99, 6
	s_add_i32 s99, s99, s94
	s_mul_hi_u32 s101, s99, 0x6080
	s_mul_i32 s100, s99, 0x6080
	s_add_u32 s100, s100, s56
	s_addc_u32 s101, s101, s57
	global_load_dword v241, v240, s[100:101]
.Lsa_skip_p3b:
.LBB0_258:
	v_add_u32_e32 v167, s75, v166
	s_mulk_i32 s96, 0x1200
	ds_read_b128 v[168:171], v167 offset:43008
	v_add3_u32 v184, v206, s96, v208
	ds_read_b128 v[172:175], v184 offset:33792
	ds_read_b128 v[176:179], v184 offset:33856
	ds_read_b128 v[180:183], v184 offset:36096
	ds_read_b128 v[184:187], v184 offset:36160
	s_mulk_i32 s95, 0x4200
	s_waitcnt lgkmcnt(4)
	v_pk_mul_f32 v[116:117], v[116:117], v[170:171]
	v_pk_mul_f32 v[114:115], v[114:115], v[168:169]
	v_pk_mul_f32 v[112:113], v[112:113], v[170:171]
	v_pk_mul_f32 v[110:111], v[110:111], v[168:169]
	s_waitcnt vmcnt(23) lgkmcnt(3)
	v_mfma_f32_16x16x32_bf16 v[114:117], v[10:13], v[172:175], v[114:117]
	v_add3_u32 v231, v165, s95, v209
	s_and_b64 vcc, exec, s[16:17]
	s_waitcnt lgkmcnt(1)
	v_mfma_f32_16x16x32_bf16 v[110:113], v[10:13], v[180:183], v[110:113]
	s_waitcnt vmcnt(22)
	v_mfma_f32_16x16x32_bf16 v[114:117], v[14:17], v[176:179], v[114:117]
	s_waitcnt lgkmcnt(0)
	v_mfma_f32_16x16x32_bf16 v[110:113], v[14:17], v[184:187], v[110:113]
	s_nop 5
	v_cvt_pk_bf16_f32 v168, v114, v115
	v_cvt_pk_bf16_f32 v169, v116, v117
	ds_write_b64 v231, v[168:169]
	v_cvt_pk_bf16_f32 v168, v110, v111
	v_cvt_pk_bf16_f32 v169, v112, v113
	ds_write_b64 v231, v[168:169] offset:8448
	ds_read_b128 v[168:171], v167 offset:43072
	s_waitcnt lgkmcnt(0)
	v_pk_mul_f32 v[120:121], v[120:121], v[170:171]
	v_pk_mul_f32 v[118:119], v[118:119], v[168:169]
	v_pk_mul_f32 v[108:109], v[108:109], v[170:171]
	v_pk_mul_f32 v[106:107], v[106:107], v[168:169]
	s_waitcnt vmcnt(21)
	v_mfma_f32_16x16x32_bf16 v[118:121], v[34:37], v[172:175], v[118:121]
	v_mfma_f32_16x16x32_bf16 v[106:109], v[34:37], v[180:183], v[106:109]
	s_waitcnt vmcnt(20)
	v_mfma_f32_16x16x32_bf16 v[118:121], v[46:49], v[176:179], v[118:121]
	v_mfma_f32_16x16x32_bf16 v[106:109], v[46:49], v[184:187], v[106:109]
	s_nop 6
	v_cvt_pk_bf16_f32 v168, v118, v119
	v_cvt_pk_bf16_f32 v169, v120, v121
	ds_write_b64 v231, v[168:169] offset:32
	v_cvt_pk_bf16_f32 v168, v106, v107
	v_cvt_pk_bf16_f32 v169, v108, v109
	ds_write_b64 v231, v[168:169] offset:8480
	ds_read_b128 v[168:171], v167 offset:43136
	s_waitcnt lgkmcnt(0)
	v_pk_mul_f32 v[136:137], v[136:137], v[170:171]
	v_pk_mul_f32 v[134:135], v[134:135], v[168:169]
	v_pk_mul_f32 v[104:105], v[104:105], v[170:171]
	v_pk_mul_f32 v[102:103], v[102:103], v[168:169]
	s_waitcnt vmcnt(19)
	v_mfma_f32_16x16x32_bf16 v[134:137], v[62:65], v[172:175], v[134:137]
	v_mfma_f32_16x16x32_bf16 v[102:105], v[62:65], v[180:183], v[102:105]
	s_waitcnt vmcnt(18)
	v_mfma_f32_16x16x32_bf16 v[134:137], v[66:69], v[176:179], v[134:137]
	v_mfma_f32_16x16x32_bf16 v[102:105], v[66:69], v[184:187], v[102:105]
	s_nop 6
	v_cvt_pk_bf16_f32 v168, v134, v135
	v_cvt_pk_bf16_f32 v169, v136, v137
	ds_write_b64 v231, v[168:169] offset:64
	v_cvt_pk_bf16_f32 v168, v102, v103
	v_cvt_pk_bf16_f32 v169, v104, v105
	ds_write_b64 v231, v[168:169] offset:8512
	ds_read_b128 v[168:171], v167 offset:43200
	s_waitcnt lgkmcnt(0)
	v_pk_mul_f32 v[132:133], v[132:133], v[170:171]
	v_pk_mul_f32 v[130:131], v[130:131], v[168:169]
	v_pk_mul_f32 v[100:101], v[100:101], v[170:171]
	v_pk_mul_f32 v[98:99], v[98:99], v[168:169]
	s_waitcnt vmcnt(17)
	v_mfma_f32_16x16x32_bf16 v[130:133], v[70:73], v[172:175], v[130:133]
	v_mfma_f32_16x16x32_bf16 v[98:101], v[70:73], v[180:183], v[98:101]
	s_waitcnt vmcnt(16)
	v_mfma_f32_16x16x32_bf16 v[130:133], v[74:77], v[176:179], v[130:133]
	v_mfma_f32_16x16x32_bf16 v[98:101], v[74:77], v[184:187], v[98:101]
	s_nop 6
	v_cvt_pk_bf16_f32 v168, v130, v131
	v_cvt_pk_bf16_f32 v169, v132, v133
	ds_write_b64 v231, v[168:169] offset:96
	v_cvt_pk_bf16_f32 v168, v98, v99
	v_cvt_pk_bf16_f32 v169, v100, v101
	ds_write_b64 v231, v[168:169] offset:8544
	s_cbranch_vccnz .LBB0_260
	v_lshl_add_u32 v167, v202, 2, s86
	s_waitcnt vmcnt(8)
	ds_write_b128 v167, v[78:81] offset:43008
.LBB0_260:
	s_cmpk_gt_u32 s74, 0x7d
	s_cbranch_scc1 .LBB0_251
	s_min_u32 s98, s74, 0x7b
	s_add_i32 s98, s98, 4
	s_lshl_b32 s99, s98, 6
	s_add_i32 s99, s99, s94
	s_mul_i32 s100, s99, 0x6080
	s_add_u32 s100, s100, s56
	s_addc_u32 s101, s57, 0
	s_waitcnt lgkmcnt(0)
	s_barrier
	global_load_dwordx4 v[10:13], v244, s[100:101]
	s_add_u32 s100, s100, 0xc000
	s_addc_u32 s101, s101, 0
	global_load_dwordx4 v[14:17], v244, s[100:101] offset:256
	s_add_u32 s100, s100, 0xc000
	s_addc_u32 s101, s101, 0
	global_load_dwordx4 v[34:37], v244, s[100:101] offset:512
	s_add_u32 s100, s100, 0xc000
	s_addc_u32 s101, s101, 0
	global_load_dwordx4 v[46:49], v244, s[100:101] offset:768
	s_add_u32 s100, s100, 0xc000
	s_addc_u32 s101, s101, 0
	global_load_dwordx4 v[62:65], v244, s[100:101] offset:1024
	s_add_u32 s100, s100, 0xc000
	s_addc_u32 s101, s101, 0
	global_load_dwordx4 v[66:69], v244, s[100:101] offset:1280
	s_add_u32 s100, s100, 0xc000
	s_addc_u32 s101, s101, 0
	global_load_dwordx4 v[70:73], v244, s[100:101] offset:1536
	s_add_u32 s100, s100, 0xc000
	s_addc_u32 s101, s101, 0
	global_load_dwordx4 v[74:77], v244, s[100:101] offset:1792
	s_and_b64 vcc, exec, s[16:17]
	s_cbranch_vccnz .Lsa_skip_p3c
	s_lshl_b32 s98, s98, 2
	s_add_i32 s100, s98, s22
	s_ashr_i32 s101, s100, 31
	s_lshl_b64 s[100:101], s[100:101], 10
	v_lshl_add_u64 v[58:59], v[158:159], 0, s[100:101]
	global_load_dwordx4 v[58:61], v[58:59], off
	s_min_u32 s99, s74, 0x7b
	s_add_i32 s99, s99, 6
	s_min_u32 s99, s99, 0x7f
	s_lshl_b32 s99, s99, 6
	s_add_i32 s99, s99, s94
	s_mul_hi_u32 s101, s99, 0x6080
	s_mul_i32 s100, s99, 0x6080
	s_add_u32 s100, s100, s56
	s_addc_u32 s101, s101, s57
	global_load_dword v241, v240, s[100:101]
.Lsa_skip_p3c:
.LBB0_263:
	ds_read_b128 v[168:171], v2 offset:43008
	ds_read_b128 v[172:175], v5 offset:33792
	ds_read_b128 v[176:179], v5 offset:33856
	ds_read_b128 v[180:183], v5 offset:36096
	s_and_b64 vcc, exec, s[16:17]
	s_waitcnt lgkmcnt(3)
	v_pk_mul_f32 v[116:117], v[116:117], v[170:171]
	v_pk_mul_f32 v[114:115], v[114:115], v[168:169]
	v_pk_mul_f32 v[112:113], v[112:113], v[170:171]
	v_pk_mul_f32 v[110:111], v[110:111], v[168:169]
	s_waitcnt vmcnt(23) lgkmcnt(2)
	v_mfma_f32_16x16x32_bf16 v[114:117], v[142:145], v[172:175], v[114:117]
	s_waitcnt lgkmcnt(0)
	v_mfma_f32_16x16x32_bf16 v[110:113], v[142:145], v[180:183], v[110:113]
	ds_read_b128 v[142:145], v5 offset:36160
	s_waitcnt vmcnt(22)
	v_mfma_f32_16x16x32_bf16 v[114:117], v[138:141], v[176:179], v[114:117]
	s_waitcnt lgkmcnt(0)
	v_mfma_f32_16x16x32_bf16 v[110:113], v[138:141], v[142:145], v[110:113]
	s_nop 5
	v_cvt_pk_bf16_f32 v168, v114, v115
	v_cvt_pk_bf16_f32 v169, v116, v117
	v_cvt_pk_bf16_f32 v138, v110, v111
	v_cvt_pk_bf16_f32 v139, v112, v113
	ds_write_b64 v4, v[168:169]
	ds_write_b64 v4, v[138:139] offset:8448
	ds_read_b128 v[138:141], v2 offset:43072
	s_waitcnt lgkmcnt(0)
	v_pk_mul_f32 v[120:121], v[120:121], v[140:141]
	v_pk_mul_f32 v[118:119], v[118:119], v[138:139]
	v_pk_mul_f32 v[108:109], v[108:109], v[140:141]
	v_pk_mul_f32 v[106:107], v[106:107], v[138:139]
	s_waitcnt vmcnt(21)
	v_mfma_f32_16x16x32_bf16 v[118:121], v[126:129], v[172:175], v[118:121]
	v_mfma_f32_16x16x32_bf16 v[106:109], v[126:129], v[180:183], v[106:109]
	s_waitcnt vmcnt(20)
	v_mfma_f32_16x16x32_bf16 v[118:121], v[122:125], v[176:179], v[118:121]
	v_mfma_f32_16x16x32_bf16 v[106:109], v[122:125], v[142:145], v[106:109]
	s_nop 6
	v_cvt_pk_bf16_f32 v126, v118, v119
	v_cvt_pk_bf16_f32 v127, v120, v121
	v_cvt_pk_bf16_f32 v122, v106, v107
	v_cvt_pk_bf16_f32 v123, v108, v109
	ds_write_b64 v4, v[126:127] offset:32
	ds_write_b64 v4, v[122:123] offset:8480
	ds_read_b128 v[122:125], v2 offset:43136
	s_waitcnt lgkmcnt(0)
	v_pk_mul_f32 v[128:129], v[136:137], v[124:125]
	v_pk_mul_f32 v[126:127], v[134:135], v[122:123]
	v_pk_mul_f32 v[104:105], v[104:105], v[124:125]
	v_pk_mul_f32 v[102:103], v[102:103], v[122:123]
	s_waitcnt vmcnt(19)
	v_mfma_f32_16x16x32_bf16 v[126:129], v[94:97], v[172:175], v[126:129]
	v_mfma_f32_16x16x32_bf16 v[94:97], v[94:97], v[180:183], v[102:105]
	s_waitcnt vmcnt(18)
	v_mfma_f32_16x16x32_bf16 v[134:137], v[90:93], v[176:179], v[126:129]
	v_mfma_f32_16x16x32_bf16 v[102:105], v[90:93], v[142:145], v[94:97]
	s_nop 6
	v_cvt_pk_bf16_f32 v122, v134, v135
	v_cvt_pk_bf16_f32 v123, v136, v137
	v_cvt_pk_bf16_f32 v90, v102, v103
	v_cvt_pk_bf16_f32 v91, v104, v105
	ds_write_b64 v4, v[122:123] offset:64
	ds_write_b64 v4, v[90:91] offset:8512
	ds_read_b128 v[90:93], v2 offset:43200
	s_waitcnt lgkmcnt(0)
	v_pk_mul_f32 v[96:97], v[132:133], v[92:93]
	v_pk_mul_f32 v[94:95], v[130:131], v[90:91]
	v_pk_mul_f32 v[92:93], v[100:101], v[92:93]
	v_pk_mul_f32 v[90:91], v[98:99], v[90:91]
	s_waitcnt vmcnt(17)
	v_mfma_f32_16x16x32_bf16 v[94:97], v[86:89], v[172:175], v[94:97]
	v_mfma_f32_16x16x32_bf16 v[86:89], v[86:89], v[180:183], v[90:93]
	s_waitcnt vmcnt(16)
	v_mfma_f32_16x16x32_bf16 v[130:133], v[82:85], v[176:179], v[94:97]
	v_mfma_f32_16x16x32_bf16 v[98:101], v[82:85], v[142:145], v[86:89]
	s_nop 6
	v_cvt_pk_bf16_f32 v90, v130, v131
	v_cvt_pk_bf16_f32 v91, v132, v133
	v_cvt_pk_bf16_f32 v82, v98, v99
	v_cvt_pk_bf16_f32 v83, v100, v101
	ds_write_b64 v4, v[90:91] offset:96
	ds_write_b64 v4, v[82:83] offset:8544
	s_cbranch_vccnz .LBB0_251
	v_add_u32_e32 v2, s75, v204
	s_waitcnt vmcnt(8)
	ds_write_b128 v2, v[6:9] offset:43008
	s_branch .LBB0_251

.LBB0_692:
	v_mov_b32_e32 v2, v1
	v_mov_b32_e32 v3, v1
	v_mov_b32_e32 v94, v1
	v_mov_b32_e32 v95, v1
	v_lshl_add_u64 v[144:145], v[0:1], 1, s[56:57]
	s_lshl_b32 s10, s13, 10
	s_lshl_b32 s11, s14, 6
	v_lshlrev_b32_e32 v205, 1, v0
	v_mov_b32_e32 v0, v1
	v_mov_b32_e32 v92, v1
	v_mov_b32_e32 v93, v1
	v_mov_b64_e32 v[130:131], v[94:95]
	v_mov_b64_e32 v[102:103], v[94:95]
	v_mov_b64_e32 v[134:135], v[94:95]
	v_mov_b64_e32 v[106:107], v[94:95]
	v_mov_b64_e32 v[118:119], v[94:95]
	v_mov_b64_e32 v[114:115], v[94:95]
	v_mov_b64_e32 v[110:111], v[94:95]
	v_mov_b64_e32 v[78:79], v[2:3]
	s_add_i32 s10, s10, s35
	v_lshl_add_u32 v149, s14, 7, v179
	v_lshl_add_u32 v150, s14, 8, v178
	s_mov_b32 s38, 0
	s_lshl_b32 s11, s11, 2
	v_mov_b64_e32 v[128:129], v[92:93]
	v_mov_b64_e32 v[100:101], v[92:93]
	v_mov_b64_e32 v[132:133], v[92:93]
	v_mov_b64_e32 v[104:105], v[92:93]
	v_mov_b64_e32 v[116:117], v[92:93]
	v_mov_b64_e32 v[112:113], v[92:93]
	v_mov_b64_e32 v[108:109], v[92:93]
	v_mov_b64_e32 v[76:77], v[0:1]
	v_and_b32_e32 v201, 63, v170
	v_bfe_u32 v202, v201, 3, 2
	s_bfe_u32 s98, s27, 0x40003
	s_and_b32 s98, s98, 15
	s_lshl_b32 s98, s98, 2
	v_add_u32_e32 v202, s98, v202
	v_mul_u32_u24_e32 v202, 0x6080, v202
	v_and_b32_e32 v203, 3, v201
	v_lshlrev_b32_e32 v203, 7, v203
	v_bfe_u32 v204, v201, 2, 1
	v_lshlrev_b32_e32 v204, 12, v204
	s_mul_i32 s99, s35, 512
	v_add3_u32 v201, v202, v203, v204
	v_add_u32_e32 v201, s99, v201
	s_branch .LBB0_694

.LBB0_694:
	s_min_u32 s98, s38, 0x7d
	s_add_i32 s98, s98, 2
	s_lshl_b32 s99, s98, 6
	s_add_i32 s99, s99, s37
	s_mul_i32 s100, s99, 0x6080
	s_add_u32 s100, s100, s56
	s_addc_u32 s101, s57, 0
	s_waitcnt lgkmcnt(0)
	s_barrier
	global_load_dwordx4 v[140:143], v205, s[100:101]
	s_add_u32 s100, s100, 0xc000
	s_addc_u32 s101, s101, 0
	global_load_dwordx4 v[136:139], v205, s[100:101] offset:256
	s_add_u32 s100, s100, 0xc000
	s_addc_u32 s101, s101, 0
	global_load_dwordx4 v[124:127], v205, s[100:101] offset:512
	s_add_u32 s100, s100, 0xc000
	s_addc_u32 s101, s101, 0
	global_load_dwordx4 v[120:123], v205, s[100:101] offset:768
	s_add_u32 s100, s100, 0xc000
	s_addc_u32 s101, s101, 0
	global_load_dwordx4 v[96:99], v205, s[100:101] offset:1024
	s_add_u32 s100, s100, 0xc000
	s_addc_u32 s101, s101, 0
	global_load_dwordx4 v[88:91], v205, s[100:101] offset:1280
	s_add_u32 s100, s100, 0xc000
	s_addc_u32 s101, s101, 0
	global_load_dwordx4 v[84:87], v205, s[100:101] offset:1536
	s_add_u32 s100, s100, 0xc000
	s_addc_u32 s101, s101, 0
	global_load_dwordx4 v[80:83], v205, s[100:101] offset:1792
	s_and_b64 vcc, exec, s[6:7]
	s_cbranch_vccnz .Lsa_skip_p9a
	s_lshl_b32 s98, s98, 3
	s_add_i32 s100, s98, s10
	s_ashr_i32 s101, s100, 31
	s_lshl_b64 s[100:101], s[100:101], 10
	v_lshl_add_u64 v[76:77], v[146:147], 0, s[100:101]
	global_load_dwordx4 v[76:79], v[76:77], off
	s_min_u32 s99, s38, 0x7d
	s_add_i32 s99, s99, 4
	s_min_u32 s99, s99, 0x7f
	s_lshl_b32 s99, s99, 6
	s_add_i32 s99, s99, s37
	s_mul_hi_u32 s101, s99, 0x6080
	s_mul_i32 s100, s99, 0x6080
	s_add_u32 s100, s100, s56
	s_addc_u32 s101, s101, s57
	global_load_dword v202, v201, s[100:101]
.Lsa_skip_p9a:
.LBB0_696:
	s_and_b32 s41, s38, 1
	s_lshl_b32 s40, s41, 10
	s_mul_i32 s39, s41, 0x1200
	s_add_i32 s40, s40, 0
	v_add_u32_e32 v0, s39, v178
	s_add_i32 s39, s11, s40
	v_add_u32_e32 v3, v0, v180
	v_lshl_add_u32 v0, v177, 2, s39
	ds_read_b128 v[152:155], v0 offset:43008
	ds_read_b128 v[156:159], v3 offset:33792
	ds_read_b128 v[160:163], v3 offset:33856
	ds_read_b128 v[164:167], v3 offset:36096
	ds_read_b128 v[196:199], v3 offset:36160
	s_xor_b32 s42, s41, 1
	s_waitcnt lgkmcnt(4)
	v_pk_mul_f32 v[110:111], v[110:111], v[154:155]
	v_pk_mul_f32 v[108:109], v[108:109], v[152:153]
	v_pk_mul_f32 v[114:115], v[114:115], v[154:155]
	v_pk_mul_f32 v[112:113], v[112:113], v[152:153]
	s_waitcnt vmcnt(15) lgkmcnt(3)
	v_mfma_f32_16x16x32_bf16 v[108:111], v[48:51], v[156:159], v[108:111]
	s_mul_i32 s39, s42, 0x4200
	v_add_u32_e32 v2, s39, v149
	v_add_u32_e32 v2, v2, v181
	s_waitcnt lgkmcnt(1)
	v_mfma_f32_16x16x32_bf16 v[48:51], v[48:51], v[164:167], v[112:115]
	s_and_b64 vcc, exec, s[6:7]
	s_lshl_b32 s39, s42, 10
	s_waitcnt vmcnt(14)
	v_mfma_f32_16x16x32_bf16 v[108:111], v[52:55], v[160:163], v[108:111]
	s_waitcnt lgkmcnt(0)
	v_mfma_f32_16x16x32_bf16 v[112:115], v[52:55], v[196:199], v[48:51]
	s_nop 5
	v_cvt_pk_bf16_f32 v168, v108, v109
	v_cvt_pk_bf16_f32 v169, v110, v111
	v_cvt_pk_bf16_f32 v48, v112, v113
	v_cvt_pk_bf16_f32 v49, v114, v115
	ds_write_b64 v2, v[168:169]
	ds_write_b64 v2, v[48:49] offset:8448
	ds_read_b128 v[48:51], v0 offset:43072
	s_waitcnt lgkmcnt(0)
	v_pk_mul_f32 v[54:55], v[118:119], v[50:51]
	v_pk_mul_f32 v[52:53], v[116:117], v[48:49]
	v_pk_mul_f32 v[50:51], v[106:107], v[50:51]
	v_pk_mul_f32 v[48:49], v[104:105], v[48:49]
	s_waitcnt vmcnt(13)
	v_mfma_f32_16x16x32_bf16 v[52:55], v[40:43], v[156:159], v[52:55]
	v_mfma_f32_16x16x32_bf16 v[40:43], v[40:43], v[164:167], v[48:51]
	s_waitcnt vmcnt(12)
	v_mfma_f32_16x16x32_bf16 v[116:119], v[44:47], v[160:163], v[52:55]
	v_mfma_f32_16x16x32_bf16 v[104:107], v[44:47], v[196:199], v[40:43]
	s_nop 6
	v_cvt_pk_bf16_f32 v48, v116, v117
	v_cvt_pk_bf16_f32 v49, v118, v119
	v_cvt_pk_bf16_f32 v40, v104, v105
	v_cvt_pk_bf16_f32 v41, v106, v107
	ds_write_b64 v2, v[48:49] offset:32
	ds_write_b64 v2, v[40:41] offset:8480
	ds_read_b128 v[40:43], v0 offset:43136
	s_waitcnt lgkmcnt(0)
	v_pk_mul_f32 v[46:47], v[134:135], v[42:43]
	v_pk_mul_f32 v[44:45], v[132:133], v[40:41]
	v_pk_mul_f32 v[42:43], v[102:103], v[42:43]
	v_pk_mul_f32 v[40:41], v[100:101], v[40:41]
	s_waitcnt vmcnt(11)
	v_mfma_f32_16x16x32_bf16 v[44:47], v[28:31], v[156:159], v[44:47]
	v_mfma_f32_16x16x32_bf16 v[28:31], v[28:31], v[164:167], v[40:43]
	s_waitcnt vmcnt(10)
	v_mfma_f32_16x16x32_bf16 v[132:135], v[32:35], v[160:163], v[44:47]
	v_mfma_f32_16x16x32_bf16 v[100:103], v[32:35], v[196:199], v[28:31]
	s_nop 6
	v_cvt_pk_bf16_f32 v40, v132, v133
	v_cvt_pk_bf16_f32 v41, v134, v135
	v_cvt_pk_bf16_f32 v28, v100, v101
	v_cvt_pk_bf16_f32 v29, v102, v103
	ds_write_b64 v2, v[40:41] offset:64
	ds_write_b64 v2, v[28:29] offset:8512
	ds_read_b128 v[28:31], v0 offset:43200
	s_waitcnt lgkmcnt(0)
	v_pk_mul_f32 v[34:35], v[130:131], v[30:31]
	v_pk_mul_f32 v[32:33], v[128:129], v[28:29]
	v_pk_mul_f32 v[30:31], v[94:95], v[30:31]
	v_pk_mul_f32 v[28:29], v[92:93], v[28:29]
	s_waitcnt vmcnt(9)
	v_mfma_f32_16x16x32_bf16 v[32:35], v[16:19], v[156:159], v[32:35]
	v_mfma_f32_16x16x32_bf16 v[16:19], v[16:19], v[164:167], v[28:31]
	s_waitcnt vmcnt(8)
	v_mfma_f32_16x16x32_bf16 v[128:131], v[20:23], v[160:163], v[32:35]
	v_mfma_f32_16x16x32_bf16 v[92:95], v[20:23], v[196:199], v[16:19]
	s_nop 6
	v_cvt_pk_bf16_f32 v28, v128, v129
	v_cvt_pk_bf16_f32 v29, v130, v131
	v_cvt_pk_bf16_f32 v16, v92, v93
	v_cvt_pk_bf16_f32 v17, v94, v95
	ds_write_b64 v2, v[28:29] offset:96
	ds_write_b64 v2, v[16:17] offset:8544
	s_cbranch_vccnz .LBB0_698
	v_add_u32_e32 v16, s39, v176
	s_waitcnt vmcnt(8)
	ds_write_b128 v16, v[60:63] offset:43008
.LBB0_698:
	s_min_u32 s98, s38, 0x7c
	s_add_i32 s98, s98, 3
	s_lshl_b32 s99, s98, 6
	s_add_i32 s99, s99, s37
	s_mul_i32 s100, s99, 0x6080
	s_add_u32 s100, s100, s56
	s_addc_u32 s101, s57, 0
	s_waitcnt lgkmcnt(0)
	s_barrier
	global_load_dwordx4 v[48:51], v205, s[100:101]
	s_add_u32 s100, s100, 0xc000
	s_addc_u32 s101, s101, 0
	global_load_dwordx4 v[52:55], v205, s[100:101] offset:256
	s_add_u32 s100, s100, 0xc000
	s_addc_u32 s101, s101, 0
	global_load_dwordx4 v[40:43], v205, s[100:101] offset:512
	s_add_u32 s100, s100, 0xc000
	s_addc_u32 s101, s101, 0
	global_load_dwordx4 v[44:47], v205, s[100:101] offset:768
	s_add_u32 s100, s100, 0xc000
	s_addc_u32 s101, s101, 0
	global_load_dwordx4 v[28:31], v205, s[100:101] offset:1024
	s_add_u32 s100, s100, 0xc000
	s_addc_u32 s101, s101, 0
	global_load_dwordx4 v[32:35], v205, s[100:101] offset:1280
	s_add_u32 s100, s100, 0xc000
	s_addc_u32 s101, s101, 0
	global_load_dwordx4 v[16:19], v205, s[100:101] offset:1536
	s_add_u32 s100, s100, 0xc000
	s_addc_u32 s101, s101, 0
	global_load_dwordx4 v[20:23], v205, s[100:101] offset:1792
	s_and_b64 vcc, exec, s[6:7]
	s_cbranch_vccnz .Lsa_skip_p9b
	s_lshl_b32 s98, s98, 3
	s_add_i32 s100, s98, s10
	s_ashr_i32 s101, s100, 31
	s_lshl_b64 s[100:101], s[100:101], 10
	v_lshl_add_u64 v[4:5], v[146:147], 0, s[100:101]
	global_load_dwordx4 v[4:7], v[4:5], off
	s_min_u32 s99, s38, 0x7c
	s_add_i32 s99, s99, 5
	s_min_u32 s99, s99, 0x7f
	s_lshl_b32 s99, s99, 6
	s_add_i32 s99, s99, s37
	s_mul_hi_u32 s101, s99, 0x6080
	s_mul_i32 s100, s99, 0x6080
	s_add_u32 s100, s100, s56
	s_addc_u32 s101, s101, s57
	global_load_dword v202, v201, s[100:101]
.Lsa_skip_p9b:
.LBB0_700:
	v_add_u32_e32 v151, s39, v150
	s_mulk_i32 s42, 0x1200
	ds_read_b128 v[152:155], v151 offset:43008
	v_add3_u32 v168, v178, s42, v180
	ds_read_b128 v[156:159], v168 offset:33792
	ds_read_b128 v[160:163], v168 offset:33856
	ds_read_b128 v[164:167], v168 offset:36096
	ds_read_b128 v[196:199], v168 offset:36160
	s_mulk_i32 s41, 0x4200
	s_waitcnt lgkmcnt(4)
	v_pk_mul_f32 v[110:111], v[110:111], v[154:155]
	v_pk_mul_f32 v[108:109], v[108:109], v[152:153]
	v_pk_mul_f32 v[114:115], v[114:115], v[154:155]
	v_pk_mul_f32 v[112:113], v[112:113], v[152:153]
	s_waitcnt vmcnt(23) lgkmcnt(3)
	v_mfma_f32_16x16x32_bf16 v[108:111], v[8:11], v[156:159], v[108:111]
	v_add3_u32 v168, v149, s41, v181
	s_and_b64 vcc, exec, s[6:7]
	s_waitcnt lgkmcnt(1)
	v_mfma_f32_16x16x32_bf16 v[112:115], v[8:11], v[164:167], v[112:115]
	s_waitcnt vmcnt(22)
	v_mfma_f32_16x16x32_bf16 v[108:111], v[12:15], v[160:163], v[108:111]
	s_waitcnt lgkmcnt(0)
	v_mfma_f32_16x16x32_bf16 v[112:115], v[12:15], v[196:199], v[112:115]
	s_nop 5
	v_cvt_pk_bf16_f32 v152, v108, v109
	v_cvt_pk_bf16_f32 v153, v110, v111
	ds_write_b64 v168, v[152:153]
	v_cvt_pk_bf16_f32 v152, v112, v113
	v_cvt_pk_bf16_f32 v153, v114, v115
	ds_write_b64 v168, v[152:153] offset:8448
	ds_read_b128 v[152:155], v151 offset:43072
	s_waitcnt lgkmcnt(0)
	v_pk_mul_f32 v[118:119], v[118:119], v[154:155]
	v_pk_mul_f32 v[116:117], v[116:117], v[152:153]
	v_pk_mul_f32 v[106:107], v[106:107], v[154:155]
	v_pk_mul_f32 v[104:105], v[104:105], v[152:153]
	s_waitcnt vmcnt(21)
	v_mfma_f32_16x16x32_bf16 v[116:119], v[24:27], v[156:159], v[116:119]
	v_mfma_f32_16x16x32_bf16 v[104:107], v[24:27], v[164:167], v[104:107]
	s_waitcnt vmcnt(20)
	v_mfma_f32_16x16x32_bf16 v[116:119], v[36:39], v[160:163], v[116:119]
	v_mfma_f32_16x16x32_bf16 v[104:107], v[36:39], v[196:199], v[104:107]
	s_nop 6
	v_cvt_pk_bf16_f32 v152, v116, v117
	v_cvt_pk_bf16_f32 v153, v118, v119
	ds_write_b64 v168, v[152:153] offset:32
	v_cvt_pk_bf16_f32 v152, v104, v105
	v_cvt_pk_bf16_f32 v153, v106, v107
	ds_write_b64 v168, v[152:153] offset:8480
	ds_read_b128 v[152:155], v151 offset:43136
	s_waitcnt lgkmcnt(0)
	v_pk_mul_f32 v[134:135], v[134:135], v[154:155]
	v_pk_mul_f32 v[132:133], v[132:133], v[152:153]
	v_pk_mul_f32 v[102:103], v[102:103], v[154:155]
	v_pk_mul_f32 v[100:101], v[100:101], v[152:153]
	s_waitcnt vmcnt(19)
	v_mfma_f32_16x16x32_bf16 v[132:135], v[56:59], v[156:159], v[132:135]
	v_mfma_f32_16x16x32_bf16 v[100:103], v[56:59], v[164:167], v[100:103]
	s_waitcnt vmcnt(18)
	v_mfma_f32_16x16x32_bf16 v[132:135], v[64:67], v[160:163], v[132:135]
	v_mfma_f32_16x16x32_bf16 v[100:103], v[64:67], v[196:199], v[100:103]
	s_nop 6
	v_cvt_pk_bf16_f32 v152, v132, v133
	v_cvt_pk_bf16_f32 v153, v134, v135
	ds_write_b64 v168, v[152:153] offset:64
	v_cvt_pk_bf16_f32 v152, v100, v101
	v_cvt_pk_bf16_f32 v153, v102, v103
	ds_write_b64 v168, v[152:153] offset:8512
	ds_read_b128 v[152:155], v151 offset:43200
	s_waitcnt lgkmcnt(0)
	v_pk_mul_f32 v[130:131], v[130:131], v[154:155]
	v_pk_mul_f32 v[128:129], v[128:129], v[152:153]
	v_pk_mul_f32 v[94:95], v[94:95], v[154:155]
	v_pk_mul_f32 v[92:93], v[92:93], v[152:153]
	s_waitcnt vmcnt(17)
	v_mfma_f32_16x16x32_bf16 v[128:131], v[68:71], v[156:159], v[128:131]
	v_mfma_f32_16x16x32_bf16 v[92:95], v[68:71], v[164:167], v[92:95]
	s_waitcnt vmcnt(16)
	v_mfma_f32_16x16x32_bf16 v[128:131], v[72:75], v[160:163], v[128:131]
	v_mfma_f32_16x16x32_bf16 v[92:95], v[72:75], v[196:199], v[92:95]
	s_nop 6
	v_cvt_pk_bf16_f32 v152, v128, v129
	v_cvt_pk_bf16_f32 v153, v130, v131
	ds_write_b64 v168, v[152:153] offset:96
	v_cvt_pk_bf16_f32 v152, v92, v93
	v_cvt_pk_bf16_f32 v153, v94, v95
	ds_write_b64 v168, v[152:153] offset:8544
	s_cbranch_vccnz .LBB0_702
	v_lshl_add_u32 v151, v174, 2, s40
	s_waitcnt vmcnt(8)
	ds_write_b128 v151, v[76:79] offset:43008
.LBB0_702:
	s_cmpk_gt_u32 s38, 0x7d
	s_cbranch_scc1 .LBB0_693
	s_min_u32 s98, s38, 0x7b
	s_add_i32 s98, s98, 4
	s_lshl_b32 s99, s98, 6
	s_add_i32 s99, s99, s37
	s_mul_i32 s100, s99, 0x6080
	s_add_u32 s100, s100, s56
	s_addc_u32 s101, s57, 0
	s_waitcnt lgkmcnt(0)
	s_barrier
	global_load_dwordx4 v[8:11], v205, s[100:101]
	s_add_u32 s100, s100, 0xc000
	s_addc_u32 s101, s101, 0
	global_load_dwordx4 v[12:15], v205, s[100:101] offset:256
	s_add_u32 s100, s100, 0xc000
	s_addc_u32 s101, s101, 0
	global_load_dwordx4 v[24:27], v205, s[100:101] offset:512
	s_add_u32 s100, s100, 0xc000
	s_addc_u32 s101, s101, 0
	global_load_dwordx4 v[36:39], v205, s[100:101] offset:768
	s_add_u32 s100, s100, 0xc000
	s_addc_u32 s101, s101, 0
	global_load_dwordx4 v[56:59], v205, s[100:101] offset:1024
	s_add_u32 s100, s100, 0xc000
	s_addc_u32 s101, s101, 0
	global_load_dwordx4 v[64:67], v205, s[100:101] offset:1280
	s_add_u32 s100, s100, 0xc000
	s_addc_u32 s101, s101, 0
	global_load_dwordx4 v[68:71], v205, s[100:101] offset:1536
	s_add_u32 s100, s100, 0xc000
	s_addc_u32 s101, s101, 0
	global_load_dwordx4 v[72:75], v205, s[100:101] offset:1792
	s_and_b64 vcc, exec, s[6:7]
	s_cbranch_vccnz .Lsa_skip_p9c
	s_lshl_b32 s98, s98, 3
	s_add_i32 s100, s98, s10
	s_ashr_i32 s101, s100, 31
	s_lshl_b64 s[100:101], s[100:101], 10
	v_lshl_add_u64 v[60:61], v[146:147], 0, s[100:101]
	global_load_dwordx4 v[60:63], v[60:61], off
	s_min_u32 s99, s38, 0x7b
	s_add_i32 s99, s99, 6
	s_min_u32 s99, s99, 0x7f
	s_lshl_b32 s99, s99, 6
	s_add_i32 s99, s99, s37
	s_mul_hi_u32 s101, s99, 0x6080
	s_mul_i32 s100, s99, 0x6080
	s_add_u32 s100, s100, s56
	s_addc_u32 s101, s101, s57
	global_load_dword v202, v201, s[100:101]
.Lsa_skip_p9c:
.LBB0_705:
	ds_read_b128 v[152:155], v0 offset:43008
	ds_read_b128 v[156:159], v3 offset:33792
	ds_read_b128 v[160:163], v3 offset:33856
	ds_read_b128 v[164:167], v3 offset:36096
	s_and_b64 vcc, exec, s[6:7]
	s_waitcnt lgkmcnt(3)
	v_pk_mul_f32 v[110:111], v[110:111], v[154:155]
	v_pk_mul_f32 v[108:109], v[108:109], v[152:153]
	v_pk_mul_f32 v[114:115], v[114:115], v[154:155]
	v_pk_mul_f32 v[112:113], v[112:113], v[152:153]
	s_waitcnt vmcnt(23) lgkmcnt(2)
	v_mfma_f32_16x16x32_bf16 v[108:111], v[140:143], v[156:159], v[108:111]
	s_waitcnt lgkmcnt(0)
	v_mfma_f32_16x16x32_bf16 v[112:115], v[140:143], v[164:167], v[112:115]
	ds_read_b128 v[140:143], v3 offset:36160
	s_waitcnt vmcnt(22)
	v_mfma_f32_16x16x32_bf16 v[108:111], v[136:139], v[160:163], v[108:111]
	s_waitcnt lgkmcnt(0)
	v_mfma_f32_16x16x32_bf16 v[112:115], v[136:139], v[140:143], v[112:115]
	s_nop 5
	v_cvt_pk_bf16_f32 v152, v108, v109
	v_cvt_pk_bf16_f32 v153, v110, v111
	v_cvt_pk_bf16_f32 v136, v112, v113
	v_cvt_pk_bf16_f32 v137, v114, v115
	ds_write_b64 v2, v[152:153]
	ds_write_b64 v2, v[136:137] offset:8448
	ds_read_b128 v[136:139], v0 offset:43072
	s_waitcnt lgkmcnt(0)
	v_pk_mul_f32 v[118:119], v[118:119], v[138:139]
	v_pk_mul_f32 v[116:117], v[116:117], v[136:137]
	v_pk_mul_f32 v[106:107], v[106:107], v[138:139]
	v_pk_mul_f32 v[104:105], v[104:105], v[136:137]
	s_waitcnt vmcnt(21)
	v_mfma_f32_16x16x32_bf16 v[116:119], v[124:127], v[156:159], v[116:119]
	v_mfma_f32_16x16x32_bf16 v[104:107], v[124:127], v[164:167], v[104:107]
	s_waitcnt vmcnt(20)
	v_mfma_f32_16x16x32_bf16 v[116:119], v[120:123], v[160:163], v[116:119]
	v_mfma_f32_16x16x32_bf16 v[104:107], v[120:123], v[140:143], v[104:107]
	s_nop 6
	v_cvt_pk_bf16_f32 v124, v116, v117
	v_cvt_pk_bf16_f32 v125, v118, v119
	v_cvt_pk_bf16_f32 v120, v104, v105
	v_cvt_pk_bf16_f32 v121, v106, v107
	ds_write_b64 v2, v[124:125] offset:32
	ds_write_b64 v2, v[120:121] offset:8480
	ds_read_b128 v[120:123], v0 offset:43136
	s_waitcnt lgkmcnt(0)
	v_pk_mul_f32 v[126:127], v[134:135], v[122:123]
	v_pk_mul_f32 v[124:125], v[132:133], v[120:121]
	v_pk_mul_f32 v[102:103], v[102:103], v[122:123]
	v_pk_mul_f32 v[100:101], v[100:101], v[120:121]
	s_waitcnt vmcnt(19)
	v_mfma_f32_16x16x32_bf16 v[124:127], v[96:99], v[156:159], v[124:127]
	v_mfma_f32_16x16x32_bf16 v[96:99], v[96:99], v[164:167], v[100:103]
	s_waitcnt vmcnt(18)
	v_mfma_f32_16x16x32_bf16 v[132:135], v[88:91], v[160:163], v[124:127]
	v_mfma_f32_16x16x32_bf16 v[100:103], v[88:91], v[140:143], v[96:99]
	s_nop 6
	v_cvt_pk_bf16_f32 v120, v132, v133
	v_cvt_pk_bf16_f32 v121, v134, v135
	v_cvt_pk_bf16_f32 v88, v100, v101
	v_cvt_pk_bf16_f32 v89, v102, v103
	ds_write_b64 v2, v[120:121] offset:64
	ds_write_b64 v2, v[88:89] offset:8512
	ds_read_b128 v[88:91], v0 offset:43200
	s_waitcnt lgkmcnt(0)
	v_pk_mul_f32 v[98:99], v[130:131], v[90:91]
	v_pk_mul_f32 v[96:97], v[128:129], v[88:89]
	v_pk_mul_f32 v[90:91], v[94:95], v[90:91]
	v_pk_mul_f32 v[88:89], v[92:93], v[88:89]
	s_waitcnt vmcnt(17)
	v_mfma_f32_16x16x32_bf16 v[96:99], v[84:87], v[156:159], v[96:99]
	v_mfma_f32_16x16x32_bf16 v[84:87], v[84:87], v[164:167], v[88:91]
	s_waitcnt vmcnt(16)
	v_mfma_f32_16x16x32_bf16 v[128:131], v[80:83], v[160:163], v[96:99]
	v_mfma_f32_16x16x32_bf16 v[92:95], v[80:83], v[140:143], v[84:87]
	s_nop 6
	v_cvt_pk_bf16_f32 v88, v128, v129
	v_cvt_pk_bf16_f32 v89, v130, v131
	v_cvt_pk_bf16_f32 v80, v92, v93
	v_cvt_pk_bf16_f32 v81, v94, v95
	ds_write_b64 v2, v[88:89] offset:96
	ds_write_b64 v2, v[80:81] offset:8544
	s_cbranch_vccnz .LBB0_693
	v_add_u32_e32 v0, s39, v176
	s_waitcnt vmcnt(8)
	ds_write_b128 v0, v[4:7] offset:43008
	s_branch .LBB0_693
